# adds: nt hint on the in1 GEMM's Z1 stores
# speedup vs baseline: 1.0023x; 1.0023x over previous
.LBB0_1161:
	v_lshl_add_u32 v162, s52, 8, v164
	v_ashrrev_i32_e32 v163, 31, v162
	v_lshlrev_b64 v[134:135], 13, v[162:163]
	v_ashrrev_i32_e32 v161, 31, v160
	v_lshl_add_u64 v[134:135], s[34:35], 0, v[134:135]
	v_cndmask_b32_e64 v1, 0, 1, s[68:69]
	v_cvt_pk_bf16_f32 v130, v138, v139
	v_cvt_pk_bf16_f32 v131, v140, v141
	v_cvt_pk_bf16_f32 v132, v142, v143
	v_cvt_pk_bf16_f32 v133, v144, v145
	v_lshl_add_u64 v[138:139], v[160:161], 1, v[134:135]
	v_cmp_ne_u32_e64 s[6:7], 1, v1
	s_andn2_b64 vcc, exec, s[68:69]
	s_mov_b64 s[0:1], -1
	global_store_dwordx4 v[138:139], v[130:133], off nt
	s_cbranch_vccnz .LBB0_1165
	v_mov_b64_e32 v[136:137], v[124:125]
	v_mov_b64_e32 v[132:133], v[128:129]
	s_and_b64 vcc, exec, s[4:5]
	v_mov_b64_e32 v[134:135], v[122:123]
	v_mov_b64_e32 v[130:131], v[126:127]
	s_cbranch_vccnz .LBB0_1164
	v_pk_mul_f32 v[136:137], v[124:125], s[86:87] op_sel_hi:[1,0]
	v_pk_mul_f32 v[134:135], v[122:123], s[86:87] op_sel_hi:[1,0]
	v_pk_mul_f32 v[132:133], v[128:129], s[86:87] op_sel_hi:[1,0]
	v_pk_mul_f32 v[130:131], v[126:127], s[86:87] op_sel_hi:[1,0]

.LBB0_1167:
	v_or_b32_e32 v126, 16, v162
	v_ashrrev_i32_e32 v127, 31, v126
	v_lshlrev_b64 v[126:127], 13, v[126:127]
	v_lshl_add_u64 v[126:127], s[34:35], 0, v[126:127]
	v_cvt_pk_bf16_f32 v122, v130, v131
	v_cvt_pk_bf16_f32 v123, v132, v133
	v_cvt_pk_bf16_f32 v124, v134, v135
	v_cvt_pk_bf16_f32 v125, v136, v137
	v_lshl_add_u64 v[130:131], v[160:161], 1, v[126:127]
	s_and_b64 vcc, exec, s[6:7]
	s_mov_b64 s[0:1], -1
	global_store_dwordx4 v[130:131], v[122:125], off nt
	s_cbranch_vccnz .LBB0_1171
	v_mov_b64_e32 v[128:129], v[116:117]
	v_mov_b64_e32 v[124:125], v[120:121]
	s_and_b64 vcc, exec, s[4:5]
	v_mov_b64_e32 v[126:127], v[114:115]
	v_mov_b64_e32 v[122:123], v[118:119]
	s_cbranch_vccnz .LBB0_1170
	v_pk_mul_f32 v[128:129], v[116:117], s[86:87] op_sel_hi:[1,0]
	v_pk_mul_f32 v[126:127], v[114:115], s[86:87] op_sel_hi:[1,0]
	v_pk_mul_f32 v[124:125], v[120:121], s[86:87] op_sel_hi:[1,0]
	v_pk_mul_f32 v[122:123], v[118:119], s[86:87] op_sel_hi:[1,0]

.LBB0_1173:
	v_or_b32_e32 v118, 32, v162
	v_ashrrev_i32_e32 v119, 31, v118
	v_lshlrev_b64 v[118:119], 13, v[118:119]
	v_lshl_add_u64 v[118:119], s[34:35], 0, v[118:119]
	v_cvt_pk_bf16_f32 v114, v122, v123
	v_cvt_pk_bf16_f32 v115, v124, v125
	v_cvt_pk_bf16_f32 v116, v126, v127
	v_cvt_pk_bf16_f32 v117, v128, v129
	v_lshl_add_u64 v[122:123], v[160:161], 1, v[118:119]
	s_and_b64 vcc, exec, s[6:7]
	s_mov_b64 s[0:1], -1
	global_store_dwordx4 v[122:123], v[114:117], off nt
	s_cbranch_vccnz .LBB0_1177
	v_mov_b64_e32 v[120:121], v[108:109]
	v_mov_b64_e32 v[116:117], v[112:113]
	s_and_b64 vcc, exec, s[4:5]
	v_mov_b64_e32 v[118:119], v[106:107]
	v_mov_b64_e32 v[114:115], v[110:111]
	s_cbranch_vccnz .LBB0_1176
	v_pk_mul_f32 v[120:121], v[108:109], s[86:87] op_sel_hi:[1,0]
	v_pk_mul_f32 v[118:119], v[106:107], s[86:87] op_sel_hi:[1,0]
	v_pk_mul_f32 v[116:117], v[112:113], s[86:87] op_sel_hi:[1,0]
	v_pk_mul_f32 v[114:115], v[110:111], s[86:87] op_sel_hi:[1,0]

.LBB0_1179:
	v_or_b32_e32 v110, 48, v162
	v_ashrrev_i32_e32 v111, 31, v110
	v_lshlrev_b64 v[110:111], 13, v[110:111]
	v_lshl_add_u64 v[110:111], s[34:35], 0, v[110:111]
	v_cvt_pk_bf16_f32 v106, v114, v115
	v_cvt_pk_bf16_f32 v107, v116, v117
	v_cvt_pk_bf16_f32 v108, v118, v119
	v_cvt_pk_bf16_f32 v109, v120, v121
	v_lshl_add_u64 v[114:115], v[160:161], 1, v[110:111]
	s_and_b64 vcc, exec, s[6:7]
	s_mov_b64 s[0:1], -1
	global_store_dwordx4 v[114:115], v[106:109], off nt
	s_cbranch_vccnz .LBB0_1183
	v_mov_b64_e32 v[112:113], v[100:101]
	v_mov_b64_e32 v[108:109], v[104:105]
	s_and_b64 vcc, exec, s[4:5]
	v_mov_b64_e32 v[110:111], v[98:99]
	v_mov_b64_e32 v[106:107], v[102:103]
	s_cbranch_vccnz .LBB0_1182
	v_pk_mul_f32 v[112:113], v[100:101], s[86:87] op_sel_hi:[1,0]
	v_pk_mul_f32 v[110:111], v[98:99], s[86:87] op_sel_hi:[1,0]
	v_pk_mul_f32 v[108:109], v[104:105], s[86:87] op_sel_hi:[1,0]
	v_pk_mul_f32 v[106:107], v[102:103], s[86:87] op_sel_hi:[1,0]

.LBB0_1185:
	v_lshlrev_b64 v[102:103], 13, v[162:163]
	v_lshl_add_u64 v[102:103], s[34:35], 0, v[102:103]
	v_cvt_pk_bf16_f32 v98, v106, v107
	v_lshl_add_u64 v[106:107], v[160:161], 1, v[102:103]
	v_add_co_u32_e32 v102, vcc, 0x100000, v106
	v_cvt_pk_bf16_f32 v99, v108, v109
	s_nop 0
	v_addc_co_u32_e32 v103, vcc, 0, v107, vcc
	v_cvt_pk_bf16_f32 v100, v110, v111
	v_cvt_pk_bf16_f32 v101, v112, v113
	s_and_b64 vcc, exec, s[6:7]
	s_mov_b64 s[0:1], -1
	global_store_dwordx4 v[102:103], v[98:101], off nt
	s_cbranch_vccnz .LBB0_1189
	v_mov_b64_e32 v[104:105], v[92:93]
	v_mov_b64_e32 v[100:101], v[96:97]
	s_and_b64 vcc, exec, s[4:5]
	v_mov_b64_e32 v[102:103], v[90:91]
	v_mov_b64_e32 v[98:99], v[94:95]
	s_cbranch_vccnz .LBB0_1188
	v_pk_mul_f32 v[104:105], v[92:93], s[86:87] op_sel_hi:[1,0]
	v_pk_mul_f32 v[102:103], v[90:91], s[86:87] op_sel_hi:[1,0]
	v_pk_mul_f32 v[100:101], v[96:97], s[86:87] op_sel_hi:[1,0]
	v_pk_mul_f32 v[98:99], v[94:95], s[86:87] op_sel_hi:[1,0]

.LBB0_1191:
	v_lshlrev_b64 v[94:95], 13, v[162:163]
	v_lshl_add_u64 v[94:95], s[34:35], 0, v[94:95]
	v_cvt_pk_bf16_f32 v90, v98, v99
	v_lshl_add_u64 v[98:99], v[160:161], 1, v[94:95]
	v_add_co_u32_e32 v94, vcc, 0x120000, v98
	v_cvt_pk_bf16_f32 v91, v100, v101
	s_nop 0
	v_addc_co_u32_e32 v95, vcc, 0, v99, vcc
	v_cvt_pk_bf16_f32 v92, v102, v103
	v_cvt_pk_bf16_f32 v93, v104, v105
	s_and_b64 vcc, exec, s[6:7]
	s_mov_b64 s[0:1], -1
	global_store_dwordx4 v[94:95], v[90:93], off nt
	s_cbranch_vccnz .LBB0_1195
	v_mov_b64_e32 v[96:97], v[76:77]
	v_mov_b64_e32 v[92:93], v[80:81]
	s_and_b64 vcc, exec, s[4:5]
	v_mov_b64_e32 v[94:95], v[74:75]
	v_mov_b64_e32 v[90:91], v[78:79]
	s_cbranch_vccnz .LBB0_1194
	v_pk_mul_f32 v[96:97], v[76:77], s[86:87] op_sel_hi:[1,0]
	v_pk_mul_f32 v[94:95], v[74:75], s[86:87] op_sel_hi:[1,0]
	v_pk_mul_f32 v[92:93], v[80:81], s[86:87] op_sel_hi:[1,0]
	v_pk_mul_f32 v[90:91], v[78:79], s[86:87] op_sel_hi:[1,0]

.LBB0_1197:
	v_lshlrev_b64 v[78:79], 13, v[162:163]
	v_lshl_add_u64 v[78:79], s[34:35], 0, v[78:79]
	v_cvt_pk_bf16_f32 v74, v90, v91
	v_lshl_add_u64 v[90:91], v[160:161], 1, v[78:79]
	v_add_co_u32_e32 v78, vcc, 0x140000, v90
	v_cvt_pk_bf16_f32 v75, v92, v93
	s_nop 0
	v_addc_co_u32_e32 v79, vcc, 0, v91, vcc
	v_cvt_pk_bf16_f32 v76, v94, v95
	v_cvt_pk_bf16_f32 v77, v96, v97
	s_and_b64 vcc, exec, s[6:7]
	s_mov_b64 s[0:1], -1
	global_store_dwordx4 v[78:79], v[74:77], off nt
	s_cbranch_vccnz .LBB0_1201
	v_mov_b64_e32 v[80:81], v[68:69]
	v_mov_b64_e32 v[76:77], v[72:73]
	s_and_b64 vcc, exec, s[4:5]
	v_mov_b64_e32 v[78:79], v[66:67]
	v_mov_b64_e32 v[74:75], v[70:71]
	s_cbranch_vccnz .LBB0_1200
	v_pk_mul_f32 v[80:81], v[68:69], s[86:87] op_sel_hi:[1,0]
	v_pk_mul_f32 v[78:79], v[66:67], s[86:87] op_sel_hi:[1,0]
	v_pk_mul_f32 v[76:77], v[72:73], s[86:87] op_sel_hi:[1,0]
	v_pk_mul_f32 v[74:75], v[70:71], s[86:87] op_sel_hi:[1,0]

.LBB0_1203:
	v_lshlrev_b64 v[70:71], 13, v[162:163]
	v_lshl_add_u64 v[70:71], s[34:35], 0, v[70:71]
	v_lshl_add_u64 v[82:83], v[160:161], 1, v[70:71]
	v_add_co_u32_e32 v70, vcc, 0x160000, v82
	v_cvt_pk_bf16_f32 v66, v74, v75
	v_cvt_pk_bf16_f32 v67, v76, v77
	v_cvt_pk_bf16_f32 v68, v78, v79
	v_cvt_pk_bf16_f32 v69, v80, v81
	v_addc_co_u32_e32 v71, vcc, 0, v83, vcc
	global_store_dwordx4 v[70:71], v[66:69], off nt
	v_mov_b32_e32 v70, 0
	s_and_b64 vcc, exec, s[8:9]
	v_mov_b32_e32 v71, v70
	v_mov_b32_e32 v72, v70
	v_mov_b32_e32 v73, v70
	v_mov_b32_e32 v66, v70
	v_mov_b32_e32 v67, v70
	v_mov_b32_e32 v68, v70
	v_mov_b32_e32 v69, v70
	s_cbranch_vccnz .LBB0_1205
	global_load_dwordx4 v[70:73], v[158:159], off offset:512
	global_load_dwordx4 v[66:69], v[158:159], off offset:528

.LBB0_1214:
	v_cvt_pk_bf16_f32 v58, v74, v75
	v_cvt_pk_bf16_f32 v59, v76, v77
	v_cvt_pk_bf16_f32 v60, v78, v79
	v_cvt_pk_bf16_f32 v61, v80, v81
	s_and_b64 vcc, exec, s[6:7]
	s_mov_b64 s[0:1], -1
	global_store_dwordx4 v[138:139], v[58:61], off offset:256 nt
	s_cbranch_vccnz .LBB0_1218
	v_mov_b64_e32 v[64:65], v[52:53]
	v_mov_b64_e32 v[60:61], v[56:57]
	s_and_b64 vcc, exec, s[4:5]
	v_mov_b64_e32 v[62:63], v[50:51]
	v_mov_b64_e32 v[58:59], v[54:55]
	s_cbranch_vccnz .LBB0_1217
	v_pk_mul_f32 v[64:65], v[52:53], s[86:87] op_sel_hi:[1,0]
	v_pk_mul_f32 v[62:63], v[50:51], s[86:87] op_sel_hi:[1,0]
	v_pk_mul_f32 v[60:61], v[56:57], s[86:87] op_sel_hi:[1,0]
	v_pk_mul_f32 v[58:59], v[54:55], s[86:87] op_sel_hi:[1,0]

.LBB0_1220:
	v_cvt_pk_bf16_f32 v50, v58, v59
	v_cvt_pk_bf16_f32 v51, v60, v61
	v_cvt_pk_bf16_f32 v52, v62, v63
	v_cvt_pk_bf16_f32 v53, v64, v65
	s_and_b64 vcc, exec, s[6:7]
	s_mov_b64 s[0:1], -1
	global_store_dwordx4 v[130:131], v[50:53], off offset:256 nt
	s_cbranch_vccnz .LBB0_1224
	v_mov_b64_e32 v[56:57], v[44:45]
	v_mov_b64_e32 v[52:53], v[48:49]
	s_and_b64 vcc, exec, s[4:5]
	v_mov_b64_e32 v[54:55], v[42:43]
	v_mov_b64_e32 v[50:51], v[46:47]
	s_cbranch_vccnz .LBB0_1223
	v_pk_mul_f32 v[56:57], v[44:45], s[86:87] op_sel_hi:[1,0]
	v_pk_mul_f32 v[54:55], v[42:43], s[86:87] op_sel_hi:[1,0]
	v_pk_mul_f32 v[52:53], v[48:49], s[86:87] op_sel_hi:[1,0]
	v_pk_mul_f32 v[50:51], v[46:47], s[86:87] op_sel_hi:[1,0]

.LBB0_1226:
	v_cvt_pk_bf16_f32 v42, v50, v51
	v_cvt_pk_bf16_f32 v43, v52, v53
	v_cvt_pk_bf16_f32 v44, v54, v55
	v_cvt_pk_bf16_f32 v45, v56, v57
	s_and_b64 vcc, exec, s[6:7]
	s_mov_b64 s[0:1], -1
	global_store_dwordx4 v[122:123], v[42:45], off offset:256 nt
	s_cbranch_vccnz .LBB0_1230
	v_mov_b64_e32 v[48:49], v[36:37]
	v_mov_b64_e32 v[44:45], v[40:41]
	s_and_b64 vcc, exec, s[4:5]
	v_mov_b64_e32 v[46:47], v[34:35]
	v_mov_b64_e32 v[42:43], v[38:39]
	s_cbranch_vccnz .LBB0_1229
	v_pk_mul_f32 v[48:49], v[36:37], s[86:87] op_sel_hi:[1,0]
	v_pk_mul_f32 v[46:47], v[34:35], s[86:87] op_sel_hi:[1,0]
	v_pk_mul_f32 v[44:45], v[40:41], s[86:87] op_sel_hi:[1,0]
	v_pk_mul_f32 v[42:43], v[38:39], s[86:87] op_sel_hi:[1,0]

.LBB0_1232:
	v_cvt_pk_bf16_f32 v34, v42, v43
	v_cvt_pk_bf16_f32 v35, v44, v45
	v_cvt_pk_bf16_f32 v36, v46, v47
	v_cvt_pk_bf16_f32 v37, v48, v49
	s_and_b64 vcc, exec, s[6:7]
	s_mov_b64 s[0:1], -1
	global_store_dwordx4 v[114:115], v[34:37], off offset:256 nt
	s_cbranch_vccnz .LBB0_1236
	v_mov_b64_e32 v[40:41], v[28:29]
	v_mov_b64_e32 v[36:37], v[32:33]
	s_and_b64 vcc, exec, s[4:5]
	v_mov_b64_e32 v[38:39], v[26:27]
	v_mov_b64_e32 v[34:35], v[30:31]
	s_cbranch_vccnz .LBB0_1235
	v_pk_mul_f32 v[40:41], v[28:29], s[86:87] op_sel_hi:[1,0]
	v_pk_mul_f32 v[38:39], v[26:27], s[86:87] op_sel_hi:[1,0]
	v_pk_mul_f32 v[36:37], v[32:33], s[86:87] op_sel_hi:[1,0]
	v_pk_mul_f32 v[34:35], v[30:31], s[86:87] op_sel_hi:[1,0]

.LBB0_1238:
	s_mov_b64 s[0:1], 0x100000
	v_lshl_add_u64 v[30:31], v[106:107], 0, s[0:1]
	v_cvt_pk_bf16_f32 v26, v34, v35
	v_cvt_pk_bf16_f32 v27, v36, v37
	v_cvt_pk_bf16_f32 v28, v38, v39
	v_cvt_pk_bf16_f32 v29, v40, v41
	s_and_b64 vcc, exec, s[6:7]
	s_mov_b64 s[0:1], -1
	global_store_dwordx4 v[30:31], v[26:29], off offset:256 nt
	s_cbranch_vccnz .LBB0_1242
	v_mov_b64_e32 v[32:33], v[20:21]
	v_mov_b64_e32 v[28:29], v[24:25]
	s_and_b64 vcc, exec, s[4:5]
	v_mov_b64_e32 v[30:31], v[18:19]
	v_mov_b64_e32 v[26:27], v[22:23]
	s_cbranch_vccnz .LBB0_1241
	v_pk_mul_f32 v[32:33], v[20:21], s[86:87] op_sel_hi:[1,0]
	v_pk_mul_f32 v[30:31], v[18:19], s[86:87] op_sel_hi:[1,0]
	v_pk_mul_f32 v[28:29], v[24:25], s[86:87] op_sel_hi:[1,0]
	v_pk_mul_f32 v[26:27], v[22:23], s[86:87] op_sel_hi:[1,0]

.LBB0_1244:
	s_mov_b64 s[0:1], 0x120000
	v_lshl_add_u64 v[22:23], v[98:99], 0, s[0:1]
	v_cvt_pk_bf16_f32 v18, v26, v27
	v_cvt_pk_bf16_f32 v19, v28, v29
	v_cvt_pk_bf16_f32 v20, v30, v31
	v_cvt_pk_bf16_f32 v21, v32, v33
	s_and_b64 vcc, exec, s[6:7]
	s_mov_b64 s[0:1], -1
	global_store_dwordx4 v[22:23], v[18:21], off offset:256 nt
	s_cbranch_vccnz .LBB0_1248
	v_mov_b64_e32 v[24:25], v[12:13]
	v_mov_b64_e32 v[20:21], v[16:17]
	s_and_b64 vcc, exec, s[4:5]
	v_mov_b64_e32 v[22:23], v[10:11]
	v_mov_b64_e32 v[18:19], v[14:15]
	s_cbranch_vccnz .LBB0_1247
	v_pk_mul_f32 v[24:25], v[12:13], s[86:87] op_sel_hi:[1,0]
	v_pk_mul_f32 v[22:23], v[10:11], s[86:87] op_sel_hi:[1,0]
	v_pk_mul_f32 v[20:21], v[16:17], s[86:87] op_sel_hi:[1,0]
	v_pk_mul_f32 v[18:19], v[14:15], s[86:87] op_sel_hi:[1,0]

.LBB0_1250:
	s_mov_b64 s[0:1], 0x140000
	v_lshl_add_u64 v[14:15], v[90:91], 0, s[0:1]
	v_cvt_pk_bf16_f32 v10, v18, v19
	v_cvt_pk_bf16_f32 v11, v20, v21
	v_cvt_pk_bf16_f32 v12, v22, v23
	v_cvt_pk_bf16_f32 v13, v24, v25
	s_and_b64 vcc, exec, s[6:7]
	s_mov_b64 s[0:1], -1
	global_store_dwordx4 v[14:15], v[10:13], off offset:256 nt
	s_cbranch_vccnz .LBB0_1254
	v_mov_b64_e32 v[16:17], v[4:5]
	v_mov_b64_e32 v[12:13], v[8:9]
	s_and_b64 vcc, exec, s[4:5]
	v_mov_b64_e32 v[14:15], v[2:3]
	v_mov_b64_e32 v[10:11], v[6:7]
	s_cbranch_vccnz .LBB0_1253
	v_pk_mul_f32 v[16:17], v[4:5], s[86:87] op_sel_hi:[1,0]
	v_pk_mul_f32 v[14:15], v[2:3], s[86:87] op_sel_hi:[1,0]
	v_pk_mul_f32 v[12:13], v[8:9], s[86:87] op_sel_hi:[1,0]
	v_pk_mul_f32 v[10:11], v[6:7], s[86:87] op_sel_hi:[1,0]

.LBB0_1256:
	s_mov_b64 s[0:1], 0x160000
	v_lshl_add_u64 v[6:7], v[82:83], 0, s[0:1]
	v_cvt_pk_bf16_f32 v2, v10, v11
	v_cvt_pk_bf16_f32 v3, v12, v13
	v_cvt_pk_bf16_f32 v4, v14, v15
	v_cvt_pk_bf16_f32 v5, v16, v17
	s_and_b64 vcc, exec, s[2:3]
	s_mov_b64 s[0:1], -1
	global_store_dwordx4 v[6:7], v[2:5], off offset:256 nt
	s_cbranch_vccnz .LBB0_1135
	s_andn2_b64 vcc, exec, s[16:17]
	s_cbranch_vccnz .LBB0_1134
	s_barrier
	s_branch .LBB0_1134
